# diff loop ring=2 (one fragment read ahead), pinned
# speedup vs baseline: 1.0044x; 1.0044x over previous
.Ldk_skip2:
	v_lshl_add_u32 v196, s11, 13, v211
	s_add_i32 s0, s40, 0xffff8000
	s_and_b32 s0, s0, 0x8000
	v_add_u32_e32 v221, s0, v216
	v_add_u32_e32 v162, v196, v212
	v_add_u32_e32 v163, v196, v213
	v_add_u32_e32 v164, v196, v214
	v_add_u32_e32 v165, v196, v215
	v_add_u32_e32 v166, v221, v217
	v_add_u32_e32 v167, v221, v218
	v_add_u32_e32 v168, v221, v219
	v_add_u32_e32 v169, v221, v220
	ds_read_b128 v[130:133], v162
	ds_read_b128 v[134:137], v162 offset:4096
	v_readlane_b32 s0, v252, 7
	s_cmpk_lt_u32 s0, 0x100
	s_cbranch_scc1 .Ldtop_skip
	s_cmp_eq_u32 s41, 2
	s_cselect_b64 s[6:7], -1, 0
	s_mov_b64 s[8:9], 0

.Ldtop_skip:
	s_setprio 1
	s_waitcnt lgkmcnt(1)
	v_mfma_f32_32x32x16_bf16 v[98:113], v[130:133], v[146:149], v[66:81]
	ds_read_b128 v[130:133], v163
	s_waitcnt lgkmcnt(1)
	v_mfma_f32_32x32x16_bf16 v[82:97], v[134:137], v[146:149], v[66:81]
	ds_read_b128 v[134:137], v163 offset:4096
	s_waitcnt lgkmcnt(1)
	v_mfma_f32_32x32x16_bf16 v[98:113], v[130:133], v[150:153], v[98:113]
	ds_read_b128 v[130:133], v164
	s_waitcnt lgkmcnt(1)
	v_mfma_f32_32x32x16_bf16 v[82:97], v[134:137], v[150:153], v[82:97]
	ds_read_b128 v[134:137], v164 offset:4096
	s_waitcnt lgkmcnt(1)
	v_mfma_f32_32x32x16_bf16 v[98:113], v[130:133], v[154:157], v[98:113]
	ds_read_b128 v[130:133], v165
	s_waitcnt lgkmcnt(1)
	v_mfma_f32_32x32x16_bf16 v[82:97], v[134:137], v[154:157], v[82:97]
	ds_read_b128 v[134:137], v165 offset:4096
	s_waitcnt lgkmcnt(1)
	v_mfma_f32_32x32x16_bf16 v[98:113], v[130:133], v[158:161], v[98:113]
	ds_read_b128 v[130:133], v166 offset:32768
	s_waitcnt lgkmcnt(1)
	v_mfma_f32_32x32x16_bf16 v[82:97], v[134:137], v[158:161], v[82:97]
	ds_read_b128 v[134:137], v166 offset:36864
	s_waitcnt lgkmcnt(1)
	v_mfma_f32_32x32x16_bf16 v[2:17], v[130:133], v[114:117], v[2:17]
	ds_read_b128 v[130:133], v166 offset:40960
	s_waitcnt lgkmcnt(1)
	v_mfma_f32_32x32x16_bf16 v[50:65], v[134:137], v[114:117], v[50:65]
	ds_read_b128 v[134:137], v166 offset:45056
	s_waitcnt lgkmcnt(1)
	v_mfma_f32_32x32x16_bf16 v[34:49], v[130:133], v[114:117], v[34:49]
	ds_read_b128 v[130:133], v167 offset:32768
	s_waitcnt lgkmcnt(1)
	v_mfma_f32_32x32x16_bf16 v[18:33], v[134:137], v[114:117], v[18:33]
	ds_read_b128 v[134:137], v167 offset:36864
	s_waitcnt lgkmcnt(1)
	v_mfma_f32_32x32x16_bf16 v[2:17], v[130:133], v[118:121], v[2:17]
	ds_read_b128 v[130:133], v167 offset:40960
	s_waitcnt lgkmcnt(1)
	v_mfma_f32_32x32x16_bf16 v[50:65], v[134:137], v[118:121], v[50:65]
	ds_read_b128 v[134:137], v167 offset:45056
	s_waitcnt lgkmcnt(1)
	v_mfma_f32_32x32x16_bf16 v[34:49], v[130:133], v[118:121], v[34:49]
	ds_read_b128 v[130:133], v168 offset:32768
	s_waitcnt lgkmcnt(1)
	v_mfma_f32_32x32x16_bf16 v[18:33], v[134:137], v[118:121], v[18:33]
	ds_read_b128 v[134:137], v168 offset:36864
	s_waitcnt lgkmcnt(1)
	v_mfma_f32_32x32x16_bf16 v[2:17], v[130:133], v[122:125], v[2:17]
	ds_read_b128 v[130:133], v168 offset:40960
	s_waitcnt lgkmcnt(1)
	v_mfma_f32_32x32x16_bf16 v[50:65], v[134:137], v[122:125], v[50:65]
	ds_read_b128 v[134:137], v168 offset:45056
	s_waitcnt lgkmcnt(1)
	v_mfma_f32_32x32x16_bf16 v[34:49], v[130:133], v[122:125], v[34:49]
	ds_read_b128 v[130:133], v169 offset:32768
	s_waitcnt lgkmcnt(1)
	v_mfma_f32_32x32x16_bf16 v[18:33], v[134:137], v[122:125], v[18:33]
	ds_read_b128 v[134:137], v169 offset:36864
	s_waitcnt lgkmcnt(1)
	v_mfma_f32_32x32x16_bf16 v[2:17], v[130:133], v[126:129], v[2:17]
	ds_read_b128 v[130:133], v169 offset:40960
	s_waitcnt lgkmcnt(1)
	v_mfma_f32_32x32x16_bf16 v[50:65], v[134:137], v[126:129], v[50:65]
	ds_read_b128 v[134:137], v169 offset:45056
	s_waitcnt lgkmcnt(1)
	v_mfma_f32_32x32x16_bf16 v[34:49], v[130:133], v[126:129], v[34:49]
	s_waitcnt lgkmcnt(0)
	v_mfma_f32_32x32x16_bf16 v[18:33], v[134:137], v[126:129], v[18:33]
	s_setprio 0
	s_addk_i32 s5, 0x4000
	s_and_b32 s0, s5, 0x4000
	v_add_u32_e32 v196, s0, v211
	v_lshl_add_u32 v221, s11, 14, v216
	v_add_u32_e32 v162, v196, v212
	v_add_u32_e32 v163, v196, v213
	v_add_u32_e32 v164, v196, v214
	v_add_u32_e32 v165, v196, v215
	v_add_u32_e32 v166, v221, v217
	v_add_u32_e32 v167, v221, v218
	v_add_u32_e32 v168, v221, v219
	v_add_u32_e32 v169, v221, v220
	ds_read_b128 v[130:133], v162
	ds_read_b128 v[134:137], v162 offset:4096
	s_mov_b64 s[6:7], 0
	s_mov_b64 s[8:9], 0

.Ldv_skip2:
	s_setprio 1
	s_waitcnt lgkmcnt(1)
	v_mfma_f32_32x32x16_bf16 v[98:113], v[130:133], v[146:149], v[66:81]
	ds_read_b128 v[130:133], v163
	s_waitcnt lgkmcnt(1)
	v_mfma_f32_32x32x16_bf16 v[82:97], v[134:137], v[146:149], v[66:81]
	ds_read_b128 v[134:137], v163 offset:4096
	s_waitcnt lgkmcnt(1)
	v_mfma_f32_32x32x16_bf16 v[98:113], v[130:133], v[150:153], v[98:113]
	ds_read_b128 v[130:133], v164
	s_waitcnt lgkmcnt(1)
	v_mfma_f32_32x32x16_bf16 v[82:97], v[134:137], v[150:153], v[82:97]
	ds_read_b128 v[134:137], v164 offset:4096
	s_waitcnt lgkmcnt(1)
	v_mfma_f32_32x32x16_bf16 v[98:113], v[130:133], v[154:157], v[98:113]
	ds_read_b128 v[130:133], v165
	s_waitcnt lgkmcnt(1)
	v_mfma_f32_32x32x16_bf16 v[82:97], v[134:137], v[154:157], v[82:97]
	ds_read_b128 v[134:137], v165 offset:4096
	s_waitcnt lgkmcnt(1)
	v_mfma_f32_32x32x16_bf16 v[98:113], v[130:133], v[158:161], v[98:113]
	ds_read_b128 v[130:133], v166 offset:32768
	s_waitcnt lgkmcnt(1)
	v_mfma_f32_32x32x16_bf16 v[82:97], v[134:137], v[158:161], v[82:97]
	ds_read_b128 v[134:137], v166 offset:36864
	s_waitcnt lgkmcnt(1)
	v_mfma_f32_32x32x16_bf16 v[2:17], v[130:133], v[114:117], v[2:17]
	ds_read_b128 v[130:133], v166 offset:40960
	s_waitcnt lgkmcnt(1)
	v_mfma_f32_32x32x16_bf16 v[50:65], v[134:137], v[114:117], v[50:65]
	ds_read_b128 v[134:137], v166 offset:45056
	s_waitcnt lgkmcnt(1)
	v_mfma_f32_32x32x16_bf16 v[34:49], v[130:133], v[114:117], v[34:49]
	ds_read_b128 v[130:133], v167 offset:32768
	s_waitcnt lgkmcnt(1)
	v_mfma_f32_32x32x16_bf16 v[18:33], v[134:137], v[114:117], v[18:33]
	ds_read_b128 v[134:137], v167 offset:36864
	s_waitcnt lgkmcnt(1)
	v_mfma_f32_32x32x16_bf16 v[2:17], v[130:133], v[118:121], v[2:17]
	ds_read_b128 v[130:133], v167 offset:40960
	s_waitcnt lgkmcnt(1)
	v_mfma_f32_32x32x16_bf16 v[50:65], v[134:137], v[118:121], v[50:65]
	ds_read_b128 v[134:137], v167 offset:45056
	s_waitcnt lgkmcnt(1)
	v_mfma_f32_32x32x16_bf16 v[34:49], v[130:133], v[118:121], v[34:49]
	ds_read_b128 v[130:133], v168 offset:32768
	s_waitcnt lgkmcnt(1)
	v_mfma_f32_32x32x16_bf16 v[18:33], v[134:137], v[118:121], v[18:33]
	ds_read_b128 v[134:137], v168 offset:36864
	s_waitcnt lgkmcnt(1)
	v_mfma_f32_32x32x16_bf16 v[2:17], v[130:133], v[122:125], v[2:17]
	ds_read_b128 v[130:133], v168 offset:40960
	s_waitcnt lgkmcnt(1)
	v_mfma_f32_32x32x16_bf16 v[50:65], v[134:137], v[122:125], v[50:65]
	ds_read_b128 v[134:137], v168 offset:45056
	s_waitcnt lgkmcnt(1)
	v_mfma_f32_32x32x16_bf16 v[34:49], v[130:133], v[122:125], v[34:49]
	ds_read_b128 v[130:133], v169 offset:32768
	s_waitcnt lgkmcnt(1)
	v_mfma_f32_32x32x16_bf16 v[18:33], v[134:137], v[122:125], v[18:33]
	ds_read_b128 v[134:137], v169 offset:36864
	s_waitcnt lgkmcnt(1)
	v_mfma_f32_32x32x16_bf16 v[2:17], v[130:133], v[126:129], v[2:17]
	ds_read_b128 v[130:133], v169 offset:40960
	s_waitcnt lgkmcnt(1)
	v_mfma_f32_32x32x16_bf16 v[50:65], v[134:137], v[126:129], v[50:65]
	ds_read_b128 v[134:137], v169 offset:45056
	s_waitcnt lgkmcnt(1)
	v_mfma_f32_32x32x16_bf16 v[34:49], v[130:133], v[126:129], v[34:49]
	s_waitcnt lgkmcnt(0)
	v_mfma_f32_32x32x16_bf16 v[18:33], v[134:137], v[126:129], v[18:33]
	s_setprio 0
	s_cmp_ge_u32 s41, s30
	s_cbranch_scc1 .Ldend_skip
	v_readlane_b32 s0, v252, 7
	s_cmpk_lt_u32 s0, 0x100
	s_cbranch_scc0 .Ldend_skip
	s_mov_b64 s[6:7], 0
	s_mov_b64 s[8:9], 0
